# v58 + RWKV last interval: state-update operand reads issued by every wave right after the barrier (own registers)
# speedup vs baseline: 1.0232x; 1.0034x over previous
; #define LAS __attribute__((address_space(3)))
; __device__ __forceinline__ f32x4 mfma16(bf16x8 a, bf16x8 b, f32x4 c) { return __builtin_amdgcn_mfma_f32_16x16x32_bf16(a, b, c, 0, 0, 0); }
; __device__ __forceinline__ void lds_barrier() { asm volatile("s_waitcnt lgkmcnt(0)" ::: "memory"); __builtin_amdgcn_s_barrier(); asm volatile("" ::: "memory"); }
; __device__ __forceinline__ void rwkv_chunk_item(const P& p, const Ctx& c, int seg, int w, bool save) {
;     ...
;     auto eload = [&](int ch) { const size_t rr = (size_t)b * SEGT + ch * 16 + et;
;         e_g = *(const u32x2*)(SG + rr * DMIX + ech); e_v = *(const u32x2*)(SV + rr * DMIX + ech); e_z = *(const u32x2*)(P2 + rr * P2W + 512 + ech); e_rkr = BRKR[(rr * 24 + hh) * 4 + 2]; };
;     ...
;         lds_barrier();
;         if (c.wv >= 4) {
;             Zt = mfma16(*(const LAS bf16x8*)(UV + (mtq * 16 + l15) * 40 + quad * 8), *(const LAS bf16x8*)(NT + l15 * 40 + quad * 8), Zt);
;             *(LAS f32x4*)(YB + l15 * 68 + mtq * 16 + quad * 4) = Zt;
;         } else eload(ch);
; #pragma unroll
;         for (int x = 0; x < 2; ++x) { const int ti = c.wv * 2 + x, mt = ti >> 2, nt = ti & 3;
;             S[x] = mfma16(*(const LAS bf16x8*)(UV + (mt * 16 + l15) * 40 + quad * 8), *(const LAS bf16x8*)(EBT + (nt * 16 + l15) * 40 + quad * 8), S[x]);
.LBB0_896:
	s_waitcnt lgkmcnt(0)
	s_barrier
	v_lshlrev_b32_e32 v52, 3, v83
	v_add_u32_e32 v136, s45, v82
	v_lshl_add_u32 v134, v52, 1, s88
	v_mov_b32_e32 v135, 0
	v_mad_u64_u32 v[136:137], s[2:3], v136, s64, v[134:135]
	ds_read_b128 v[130:133], v136 offset:14336
	v_add_u32_e32 v138, s34, v82
	v_mad_u64_u32 v[136:137], s[2:3], v138, s64, v[134:135]
	ds_read_b128 v[148:151], v136 offset:9216
	v_add_u32_e32 v136, s66, v82
	v_mad_u64_u32 v[136:137], s[2:3], v136, s64, v[134:135]
	ds_read_b128 v[124:127], v136 offset:9216
	v_lshl_add_u32 v128, v138, 2, s88
	v_add_u32_e32 v128, 0x5800, v128
	ds_read2_b32 v[152:153], v128 offset0:192 offset1:208
	s_mov_b64 s[2:3], -1
	s_and_b64 vcc, exec, s[68:69]
	v_lshlrev_b32_e32 v52, 3, v83
	s_cbranch_vccz .LBB0_898
	v_lshl_add_u64 v[44:45], v[36:37], 0, s[12:13]
	v_add_co_u32_e32 v46, vcc, 0xe900000, v44
	s_mov_b64 s[2:3], 0
	s_nop 0
	v_addc_co_u32_e32 v47, vcc, 0, v45, vcc
	v_add_co_u32_e32 v44, vcc, 0xdd00000, v44
	s_nop 1
	v_addc_co_u32_e32 v45, vcc, 0, v45, vcc
	global_load_dwordx2 v[50:51], v[46:47], off
	global_load_dwordx2 v[48:49], v[44:45], off
	v_lshl_add_u64 v[44:45], v[34:35], 0, s[12:13]
	global_load_dwordx2 v[46:47], v[44:45], off
	v_lshl_add_u64 v[44:45], v[32:33], 0, s[12:13]
	global_load_dword v44, v[44:45], off
	v_lshlrev_b32_e32 v45, 3, v83

; #define LAS __attribute__((address_space(3)))
; __device__ __forceinline__ bf16_t f2bf(float f) { const __bf16 r = (__bf16)f; bf16_t u; __builtin_memcpy(&u, &r, 2); return u; }
; __device__ __forceinline__ f32x4 mfma16(bf16x8 a, bf16x8 b, f32x4 c) { return __builtin_amdgcn_mfma_f32_16x16x32_bf16(a, b, c, 0, 0, 0); }
; __device__ __forceinline__ void rwkv_chunk_item(const P& p, const Ctx& c, int seg, int w, bool save) {
;     ...
;     auto gtile = [&](int pb, int l15, int quad) {
;         LAS bf16_t* EA = (LAS bf16_t*)(OB + pb * OPB + O_EA); LAS bf16_t* EB = (LAS bf16_t*)(OB + pb * OPB + O_EB);
;         LAS bf16_t* MT1 = (LAS bf16_t*)(OB + pb * OPB + O_MT1); LAS bf16_t* NT = (LAS bf16_t*)(OB + pb * OPB + O_NT); LAS float* MABT = (LAS float*)(OB + pb * OPB + O_MABT);
;         const int sb = c.wv >> 1, tb = c.wv & 1; f32x4 g = (f32x4){0.f, 0.f, 0.f, 0.f};
; #pragma unroll
;         for (int kk = 0; kk < 2; ++kk) g = mfma16(*(const LAS bf16x8*)(EB + (sb * 16 + l15) * 72 + kk * 32 + quad * 8), *(const LAS bf16x8*)(EA + (tb * 16 + l15) * 72 + kk * 32 + quad * 8), g);
; #pragma unroll
;         for (int jj = 0; jj < 4; ++jj) { const int s2 = quad * 4 + jj, tt = l15; const float v = g[jj];
;             if (tb == 0) { const float m = (s2 < tt) ? v : 0.f; if (sb == 0) { MABT[s2 * 20 + tt] = m; MT1[tt * 40 + s2] = 0; } else MT1[tt * 40 + 16 + s2] = f2bf(m); }
;             else { const float m = (s2 <= tt) ? v : 0.f; NT[tt * 40 + sb * 16 + s2] = f2bf(m); } } };
;     ...
; #pragma unroll
;         for (int x = 0; x < 2; ++x) { const int ti = c.wv * 2 + x, mt = ti >> 2, nt = ti & 3;
;             S[x] = mfma16(*(const LAS bf16x8*)(UV + (mt * 16 + l15) * 40 + quad * 8), *(const LAS bf16x8*)(EBT + (nt * 16 + l15) * 40 + quad * 8), S[x]);
;             const float gt = GT[nt * 16 + l15];
; #pragma unroll
;             for (int jj = 0; jj < 4; ++jj) S[x][jj] *= gt; }
;         simg(l15, quad);
;         if (c.wv < 4 && ch + 1 < SEGT / 16) gtile(pb ^ 1, l15, quad);
.LBB0_900:
	s_waitcnt lgkmcnt(2)
	v_mfma_f32_16x16x32_bf16 v[6:9], v[130:133], v[148:151], v[6:9]
	s_waitcnt lgkmcnt(0)
	v_mfma_f32_16x16x32_bf16 v[10:13], v[130:133], v[124:127], v[10:13]
	v_mov_b32_e32 v2, v153
	v_lshlrev_b32_e32 v38, 2, v83
	s_nop 7
	v_pk_mul_f32 v[6:7], v[152:153], v[6:7] op_sel_hi:[0,1]
	s_nop 4
	v_pk_mul_f32 v[10:11], v[2:3], v[10:11] op_sel_hi:[0,1]
	v_pk_mul_f32 v[12:13], v[2:3], v[12:13] op_sel_hi:[0,1]
	v_add_u32_e32 v2, s45, v38
	v_lshlrev_b32_e32 v22, 1, v82
	v_mul_lo_u32 v2, v2, s63
	v_pk_mul_f32 v[8:9], v[152:153], v[8:9] op_sel_hi:[0,1]
	v_add3_u32 v2, s40, v22, v2
	v_and_b32_e32 v140, 1, v82
	v_cmp_ne_u32_e64 s[2:3], 0, v140
	v_mov_b32_e32 v141, 0x5040100
	v_mov_b32_e32 v142, 0x3020706
	v_mul_u32_u24_e32 v140, 0x11e, v140
	v_cndmask_b32_e64 v141, v141, v142, s[2:3]
	v_add_u32_e32 v140, v2, v140
	v_cvt_pk_bf16_f32 v22, v6, v8
	v_cvt_pk_bf16_f32 v23, v7, v9
	v_cvt_pk_bf16_f32 v142, v10, v12
	v_cvt_pk_bf16_f32 v143, v11, v13
	v_mov_b32_dpp v144, v22 quad_perm:[1,0,3,2] row_mask:0xf bank_mask:0xf bound_ctrl:1
	v_mov_b32_dpp v145, v23 quad_perm:[1,0,3,2] row_mask:0xf bank_mask:0xf bound_ctrl:1
	v_mov_b32_dpp v146, v142 quad_perm:[1,0,3,2] row_mask:0xf bank_mask:0xf bound_ctrl:1
	v_mov_b32_dpp v147, v143 quad_perm:[1,0,3,2] row_mask:0xf bank_mask:0xf bound_ctrl:1
	v_perm_b32 v22, v144, v22, v141
	v_perm_b32 v23, v145, v23, v141
	v_perm_b32 v142, v146, v142, v141
	v_perm_b32 v143, v147, v143, v141
	s_or_b64 s[2:3], s[56:57], s[4:5]
	ds_write_b32 v140, v22 offset:47104
	ds_write_b32 v140, v23 offset:47248
	ds_write_b32 v140, v142 offset:47136
	s_and_b64 vcc, exec, s[2:3]
	ds_write_b32 v140, v143 offset:47280
	s_cbranch_vccnz .LBB0_929
	s_xor_b32 s2, s87, 1
	s_mulk_i32 s2, 0x5c00
	v_add_u32_e32 v2, s67, v82
	s_add_i32 s4, s2, 0
	v_mul_lo_u32 v2, v2, s63
	v_lshlrev_b32_e32 v22, 1, v45
	v_add_u32_e32 v23, s83, v82
	v_add3_u32 v2, s4, v2, v22
	v_mul_lo_u32 v23, v23, s63
	v_add3_u32 v39, s4, v23, v22
	ds_read_b128 v[22:25], v2 offset:4608
	ds_read_b128 v[40:43], v39
	ds_read_b128 v[124:127], v2 offset:4672
	ds_read_b128 v[86:89], v39 offset:64
	s_waitcnt lgkmcnt(2)
	v_mfma_f32_16x16x32_bf16 v[22:25], v[22:25], v[40:43], 0
	v_add_u32_e32 v39, s4, v84
	v_add_u32_e32 v2, s84, v39
	s_waitcnt lgkmcnt(0)
	v_mfma_f32_16x16x32_bf16 v[22:25], v[124:127], v[86:89], v[22:25]
	v_lshl_add_u32 v40, v38, 1, v2
	v_lshl_add_u32 v41, v38, 1, v39
	v_lshl_add_u32 v2, v82, 2, s4
	v_or_b32_e32 v42, 1, v38
	v_or_b32_e32 v43, 2, v38
	v_or_b32_e32 v140, 3, v38
	s_and_b64 vcc, exec, s[72:73]
	s_nop 3
	s_cbranch_vccz .Lrw_mb_notA
	v_cmp_le_i32_e32 vcc, v38, v82
	s_nop 1
	v_cndmask_b32_e32 v22, 0, v22, vcc
	v_cmp_le_i32_e32 vcc, v42, v82
	s_nop 1
	v_cndmask_b32_e32 v23, 0, v23, vcc
	v_cmp_le_i32_e32 vcc, v43, v82
	s_nop 1
	v_cndmask_b32_e32 v24, 0, v24, vcc
	v_cmp_le_i32_e32 vcc, v140, v82
	s_nop 1
	v_cndmask_b32_e32 v25, 0, v25, vcc
	v_cvt_pk_bf16_f32 v22, v22, v23
	v_cvt_pk_bf16_f32 v24, v24, v25
	ds_write_b32 v40, v22 offset:20736
	ds_write_b32 v40, v24 offset:20740
	s_branch .LBB0_929
